# v36 with 1024 W_up layer-0 items moved back from the NSA-in idle-window stub to phase 0 (lighter stub)
# speedup vs baseline: 1.0002x; 1.0002x over previous
.LBB0_13:
	s_cmp_lg_u32 s101, 0
	s_cbranch_scc1 .Lp0_noskip
	s_cmpk_lt_i32 s83, 0x780
	s_cbranch_scc1 .Lp0_noskip
	s_cmpk_lt_i32 s83, 0x1c00
	s_cbranch_scc1 .LBB0_12

.LBB0_640:
	s_waitcnt vmcnt(0)
	s_barrier
	s_cmpk_lt_u32 s86, 203
	s_cbranch_scc1 .Lcv1_skip
	v_writelane_b32 v200, s2, 0
	v_writelane_b32 v200, s3, 1
	v_writelane_b32 v200, s4, 2
	v_writelane_b32 v200, s5, 3
	v_writelane_b32 v200, s6, 4
	v_writelane_b32 v200, s7, 5
	v_writelane_b32 v200, s8, 6
	v_writelane_b32 v200, s9, 7
	v_writelane_b32 v200, s10, 8
	v_writelane_b32 v200, s11, 9
	v_writelane_b32 v200, s12, 10
	v_writelane_b32 v200, s13, 11
	v_writelane_b32 v200, s14, 12
	v_writelane_b32 v200, s15, 13
	v_writelane_b32 v200, s16, 14
	v_writelane_b32 v200, s17, 15
	v_writelane_b32 v200, s18, 16
	v_writelane_b32 v200, s19, 17
	v_writelane_b32 v200, s20, 18
	v_writelane_b32 v200, s21, 19
	v_writelane_b32 v200, s22, 20
	v_writelane_b32 v200, s23, 21
	v_writelane_b32 v200, s24, 22
	v_writelane_b32 v200, s25, 23
	v_writelane_b32 v200, s26, 24
	v_writelane_b32 v200, s27, 25
	v_writelane_b32 v200, s28, 26
	v_writelane_b32 v200, s29, 27
	v_writelane_b32 v200, s30, 28
	v_writelane_b32 v200, s31, 29
	v_writelane_b32 v200, s32, 30
	v_writelane_b32 v200, s33, 31
	v_writelane_b32 v200, s34, 32
	v_writelane_b32 v200, s35, 33
	v_writelane_b32 v200, s36, 34
	v_writelane_b32 v200, s37, 35
	v_writelane_b32 v200, s38, 36
	v_writelane_b32 v200, s39, 37
	v_writelane_b32 v200, s40, 38
	v_writelane_b32 v200, s41, 39
	v_writelane_b32 v200, s42, 40
	v_writelane_b32 v200, s43, 41
	v_writelane_b32 v200, s44, 42
	v_writelane_b32 v200, s45, 43
	v_writelane_b32 v200, s46, 44
	v_writelane_b32 v200, s47, 45
	v_writelane_b32 v200, s48, 46
	v_writelane_b32 v200, s49, 47
	v_writelane_b32 v200, s50, 48
	v_writelane_b32 v200, s51, 49
	v_writelane_b32 v200, s52, 50
	v_writelane_b32 v200, s53, 51
	v_writelane_b32 v200, s54, 52
	v_writelane_b32 v200, s55, 53
	v_writelane_b32 v200, s56, 54
	v_writelane_b32 v200, s57, 55
	v_writelane_b32 v200, s58, 56
	v_writelane_b32 v200, s59, 57
	v_writelane_b32 v200, s60, 58
	v_writelane_b32 v200, s61, 59
	v_writelane_b32 v200, s62, 60
	v_writelane_b32 v200, s63, 61
	v_writelane_b32 v200, s64, 62
	v_writelane_b32 v200, s65, 63
	v_writelane_b32 v201, s66, 0
	v_writelane_b32 v201, s67, 1
	v_writelane_b32 v201, s68, 2
	v_writelane_b32 v201, s69, 3
	v_writelane_b32 v201, s70, 4
	v_writelane_b32 v201, s71, 5
	v_writelane_b32 v201, s72, 6
	v_writelane_b32 v201, s73, 7
	v_writelane_b32 v201, s74, 8
	v_writelane_b32 v201, s75, 9
	v_writelane_b32 v201, s76, 10
	v_writelane_b32 v201, s77, 11
	v_writelane_b32 v201, s78, 12
	v_writelane_b32 v201, s79, 13
	v_writelane_b32 v201, s80, 14
	v_writelane_b32 v201, s81, 15
	v_writelane_b32 v201, s82, 16
	v_writelane_b32 v201, s83, 17
	v_writelane_b32 v201, s84, 18
	v_writelane_b32 v201, s85, 19
	v_writelane_b32 v201, s86, 20
	v_writelane_b32 v201, s87, 21
	v_writelane_b32 v201, s88, 22
	v_writelane_b32 v201, s89, 23
	v_writelane_b32 v201, s90, 24
	v_writelane_b32 v201, s91, 25
	v_writelane_b32 v201, s92, 26
	v_writelane_b32 v201, s93, 27
	v_writelane_b32 v201, s94, 28
	v_writelane_b32 v201, s95, 29
	v_writelane_b32 v201, s96, 30
	v_writelane_b32 v201, s97, 31
	v_writelane_b32 v201, s98, 32
	v_writelane_b32 v201, s99, 33
	v_mbcnt_lo_u32_b32 v0, -1, 0
	v_mbcnt_hi_u32_b32 v0, -1, v0
	v_and_b32_e32 v21, 31, v0
	v_bfe_u32 v31, v0, 5, 1
	v_lshlrev_b32_e32 v2, 2, v21
	v_mul_u32_u24_e32 v3, 0x84, v31
	v_bfe_u32 v29, v0, 3, 3
	s_lshl_b32 s2, s87, 14
	s_add_i32 s3, s2, 0
	v_add3_u32 v28, s3, v2, v3
	v_lshlrev_b32_e32 v2, 3, v0
	v_and_b32_e32 v2, 56, v2
	v_mul_u32_u24_e32 v4, 0x84, v2
	v_lshlrev_b32_e32 v5, 2, v29
	s_mov_b32 s7, 0
	v_mov_b32_e32 v3, 0
	v_add3_u32 v30, s3, v4, v5
	v_lshlrev_b32_e32 v18, 1, v2
	s_sub_i32 s2, s86, 203
	s_lshl_b32 s2, s2, 3
	s_add_i32 s2, s2, s87
	s_addk_i32 s2, 0x1000
	s_movk_i32 s43, 0x1a8
	s_movk_i32 s100, 0x1bff
	s_mov_b32 s101, 1
	s_branch .Lcv_loop_entry
